# x3 + no K-loop s_setprio flips + 4 more 1/sqrtf chains (in-proj x3, up x1 epilogues) replaced by v_rsq_f32
# speedup vs baseline: 1.0168x; 1.0053x over previous
.LBB0_562:
	s_nop 1
	v_mov_b32_e32 v118, v171
	s_nop 0
	v_add_u32_e32 v116, 16, v169
	v_and_b32_e32 v121, 63, v116
	v_add_u32_e32 v116, 16, v150
	v_ashrrev_i32_e32 v117, 31, v116
	v_lshlrev_b64 v[126:127], 13, v[116:117]
	v_fmamk_f32 v118, v118, 0x3a800000, v208
	s_nop 0
	s_nop 0
	s_nop 0
	s_nop 1
	s_nop 1
	s_movk_i32 s12, 0x1ff0
	v_lshlrev_b64 v[124:125], 11, v[116:117]
	v_and_b32_e32 v117, 0x1fff, v116
	v_ashrrev_i32_e32 v116, 13, v116
	v_rsq_f32_e32 v118, v118
	s_nop 0
	v_cmp_lt_u32_e64 s[14:15], s12, v117
	v_mul_i32_i24_e32 v116, 15, v116
	s_movk_i32 s12, 0xe00f
	v_mul_f32_e32 v119, 0x3e38aa3b, v118
	v_add3_u32 v116, v117, v116, s12
	v_cndmask_b32_e64 v134, v118, v119, s[6:7]
	v_add_u32_e32 v118, 0xffff0010, v150
	v_ashrrev_i32_e32 v117, 31, v116
	v_lshlrev_b64 v[154:155], 11, v[116:117]
	v_ashrrev_i32_e32 v116, 6, v118
	v_subrev_u32_e32 v122, 49, v121
	v_mad_u64_u32 v[116:117], s[16:17], v116, 15, v[122:123]
	v_ashrrev_i32_e32 v119, 31, v118
	v_ashrrev_i32_e32 v117, 31, v116
	v_lshlrev_b64 v[132:133], 11, v[118:119]
	v_cmp_lt_u32_e64 s[12:13], 48, v121
	v_lshlrev_b64 v[156:157], 11, v[116:117]
	v_pk_mul_f32 v[114:115], v[114:115], v[134:135] op_sel_hi:[1,0]
	v_pk_mul_f32 v[112:113], v[112:113], v[134:135] op_sel_hi:[1,0]
	v_pk_mul_f32 v[118:119], v[110:111], v[134:135] op_sel_hi:[1,0]
	v_pk_mul_f32 v[116:117], v[108:109], v[134:135] op_sel_hi:[1,0]
	s_mov_b64 s[16:17], -1
	s_and_b64 vcc, exec, s[8:9]
	v_cvt_pk_bf16_f32 v108, v112, v113
	v_cvt_pk_bf16_f32 v109, v114, v115
	v_cvt_pk_bf16_f32 v110, v116, v117
	v_cvt_pk_bf16_f32 v111, v118, v119
	s_cbranch_vccnz .LBB0_569
	s_mov_b64 s[86:87], -1
	s_mov_b64 s[16:17], 0
	s_cmp_lt_i32 s75, 2
	s_mov_b64 s[18:19], 0
	s_cbranch_scc0 .LBB0_717
	s_and_b64 vcc, exec, s[86:87]
	s_cbranch_vccnz .LBB0_720

.LBB0_580:
	s_nop 1
	v_mov_b32_e32 v102, v176
	s_nop 0
	v_add_u32_e32 v100, 32, v150
	v_ashrrev_i32_e32 v101, 31, v100
	v_xor_b32_e32 v104, 32, v170
	v_fmamk_f32 v102, v102, 0x3a800000, v208
	s_nop 0
	s_nop 0
	s_nop 0
	s_nop 1
	s_nop 1
	s_movk_i32 s14, 0x1ff0
	v_lshlrev_b64 v[108:109], 13, v[100:101]
	v_lshlrev_b64 v[106:107], 11, v[100:101]
	v_and_b32_e32 v101, 0x1fff, v100
	v_ashrrev_i32_e32 v100, 13, v100
	v_rsq_f32_e32 v102, v102
	s_nop 0
	v_cmp_lt_u32_e64 s[16:17], s14, v101
	v_mul_i32_i24_e32 v100, 15, v100
	s_movk_i32 s14, 0xe00f
	v_mul_f32_e32 v103, 0x3e38aa3b, v102
	v_add3_u32 v100, v101, v100, s14
	v_cndmask_b32_e64 v112, v102, v103, s[6:7]
	v_add_u32_e32 v102, 0xffff0020, v150
	v_ashrrev_i32_e32 v101, 31, v100
	v_lshlrev_b64 v[114:115], 11, v[100:101]
	v_cmp_lt_u32_e64 s[14:15], 48, v104
	v_ashrrev_i32_e32 v100, 6, v102
	v_subrev_u32_e32 v104, 49, v104
	v_mad_u64_u32 v[100:101], s[18:19], v100, 15, v[104:105]
	v_ashrrev_i32_e32 v103, 31, v102
	v_ashrrev_i32_e32 v101, 31, v100
	v_lshlrev_b64 v[110:111], 11, v[102:103]
	v_lshlrev_b64 v[116:117], 11, v[100:101]
	v_pk_mul_f32 v[98:99], v[98:99], v[112:113] op_sel_hi:[1,0]
	v_pk_mul_f32 v[96:97], v[96:97], v[112:113] op_sel_hi:[1,0]
	v_pk_mul_f32 v[102:103], v[94:95], v[112:113] op_sel_hi:[1,0]
	v_pk_mul_f32 v[100:101], v[92:93], v[112:113] op_sel_hi:[1,0]
	s_mov_b64 s[18:19], -1
	s_and_b64 vcc, exec, s[8:9]
	v_cvt_pk_bf16_f32 v92, v96, v97
	v_cvt_pk_bf16_f32 v93, v98, v99
	v_cvt_pk_bf16_f32 v94, v100, v101
	v_cvt_pk_bf16_f32 v95, v102, v103
	s_cbranch_vccnz .LBB0_587
	s_mov_b64 s[88:89], -1
	s_mov_b64 s[18:19], 0
	s_cmp_lt_i32 s75, 2
	s_mov_b64 s[86:87], 0
	s_cbranch_scc0 .LBB0_743
	s_and_b64 vcc, exec, s[88:89]
	s_cbranch_vccnz .LBB0_746

.LBB0_598:
	s_nop 1
	v_mov_b32_e32 v86, v177
	s_nop 0
	v_add_u32_e32 v84, 48, v169
	v_and_b32_e32 v88, 63, v84
	v_add_u32_e32 v84, 48, v150
	v_ashrrev_i32_e32 v85, 31, v84
	s_mov_b64 s[86:87], -1
	v_fmamk_f32 v86, v86, 0x3a800000, v208
	s_nop 0
	s_nop 0
	s_nop 0
	s_nop 1
	s_nop 1
	s_movk_i32 s16, 0x1ff0
	v_lshlrev_b64 v[92:93], 13, v[84:85]
	v_lshlrev_b64 v[90:91], 11, v[84:85]
	v_and_b32_e32 v85, 0x1fff, v84
	v_ashrrev_i32_e32 v84, 13, v84
	v_rsq_f32_e32 v86, v86
	s_nop 0
	v_cmp_lt_u32_e64 s[18:19], s16, v85
	v_mul_i32_i24_e32 v84, 15, v84
	s_movk_i32 s16, 0xe00f
	v_mul_f32_e32 v87, 0x3e38aa3b, v86
	v_add3_u32 v84, v85, v84, s16
	v_cndmask_b32_e64 v96, v86, v87, s[6:7]
	v_add_u32_e32 v86, 0xffff0030, v150
	v_ashrrev_i32_e32 v85, 31, v84
	v_lshlrev_b64 v[98:99], 11, v[84:85]
	v_cmp_lt_u32_e64 s[16:17], 48, v88
	v_ashrrev_i32_e32 v84, 6, v86
	v_subrev_u32_e32 v88, 49, v88
	v_mad_u64_u32 v[84:85], s[22:23], v84, 15, v[88:89]
	v_ashrrev_i32_e32 v87, 31, v86
	v_ashrrev_i32_e32 v85, 31, v84
	v_lshlrev_b64 v[94:95], 11, v[86:87]
	v_lshlrev_b64 v[100:101], 11, v[84:85]
	v_pk_mul_f32 v[82:83], v[82:83], v[96:97] op_sel_hi:[1,0]
	v_pk_mul_f32 v[80:81], v[80:81], v[96:97] op_sel_hi:[1,0]
	v_pk_mul_f32 v[86:87], v[78:79], v[96:97] op_sel_hi:[1,0]
	v_pk_mul_f32 v[84:85], v[76:77], v[96:97] op_sel_hi:[1,0]
	s_and_b64 vcc, exec, s[8:9]
	v_cvt_pk_bf16_f32 v76, v80, v81
	v_cvt_pk_bf16_f32 v77, v82, v83
	v_cvt_pk_bf16_f32 v78, v84, v85
	v_cvt_pk_bf16_f32 v79, v86, v87
	s_cbranch_vccnz .LBB0_605
	s_mov_b64 vcc, -1
	s_mov_b64 s[86:87], 0
	s_cmp_lt_i32 s75, 2
	s_mov_b64 s[88:89], 0
	s_cbranch_scc0 .LBB0_769
	s_and_b64 vcc, exec, vcc
	s_cbranch_vccnz .LBB0_772

.LBB0_2543:
	s_lshl_b32 s4, s48, 8
	v_mov_b32_e32 v2, v1
	v_mov_b32_e32 v145, v150
	s_add_i32 s4, s4, s40
	s_lshl_b32 s26, s45, 8
	v_add_u32_e32 v144, s4, v2
	v_lshlrev_b32_e32 v148, 3, v145
	v_ashrrev_i32_e32 v145, 31, v144
	v_lshl_add_u64 v[146:147], v[144:145], 2, s[2:3]
	v_mov_b32_e32 v2, v232
	v_mov_b32_e32 v158, v233
	v_mov_b32_e32 v159, v234
	v_mov_b32_e32 v160, v235
	v_mov_b32_e32 v161, v236
	v_mov_b32_e32 v162, v237
	v_mov_b32_e32 v163, v238
	v_mov_b32_e32 v164, v239
	s_ashr_i32 s27, s26, 31
	s_lshl_b64 s[26:27], s[26:27], 1
	v_ashrrev_i32_e32 v149, 31, v148
	s_cmp_eq_u32 s44, 15
	s_waitcnt vmcnt(8)
	v_fmamk_f32 v2, v2, 0x3a800000, v208
	s_nop 0
	s_nop 0
	s_nop 0
	s_nop 1
	s_nop 1
	s_nop 0
	v_rsq_f32_e32 v2, v2
	s_nop 0
	v_pk_mul_f32 v[126:127], v[126:127], v[2:3] op_sel_hi:[1,0]
	v_pk_mul_f32 v[124:125], v[124:125], v[2:3] op_sel_hi:[1,0]
	v_pk_mul_f32 v[130:131], v[130:131], v[2:3] op_sel_hi:[1,0]
	v_pk_mul_f32 v[128:129], v[128:129], v[2:3] op_sel_hi:[1,0]
	v_max_f32_e32 v124, 0, v124
	v_max_f32_e32 v125, 0, v125
	v_max_f32_e32 v126, 0, v126
	v_max_f32_e32 v128, 0, v128
	v_mul_f32_e32 v153, v124, v124
	v_max_f32_e32 v124, 0, v129
	v_mul_f32_e32 v129, v125, v125
	v_max_f32_e32 v125, 0, v130
	v_mul_f32_e32 v130, v126, v126
	v_max_f32_e32 v126, 0, v131
	v_mul_f32_e32 v128, v128, v128
	v_mul_f32_e32 v124, v124, v124
	v_mul_f32_e32 v125, v125, v125
	v_mul_f32_e32 v126, v126, v126
	v_cvt_pk_bf16_f32 v124, v128, v124
	v_cvt_pk_bf16_f32 v125, v125, v126
	v_cvt_pk_bf16_f32 v126, v153, v129
	v_lshlrev_b64 v[128:129], 13, v[144:145]
	v_max_f32_e32 v127, 0, v127
	v_lshl_add_u64 v[128:129], s[0:1], 0, v[128:129]
	v_pk_mul_f32 v[118:119], v[118:119], v[2:3] op_sel_hi:[1,0]
	v_pk_mul_f32 v[116:117], v[116:117], v[2:3] op_sel_hi:[1,0]
	v_mul_f32_e32 v127, v127, v127
	v_lshl_add_u64 v[128:129], v[128:129], 0, s[26:27]
	v_pk_mul_f32 v[122:123], v[122:123], v[2:3] op_sel_hi:[1,0]
	v_pk_mul_f32 v[120:121], v[120:121], v[2:3] op_sel_hi:[1,0]
	v_max_f32_e32 v116, 0, v116
	v_max_f32_e32 v117, 0, v117
	v_max_f32_e32 v118, 0, v118
	v_cvt_pk_bf16_f32 v127, v130, v127
	v_lshl_add_u64 v[130:131], v[128:129], 0, s[46:47]
	v_lshlrev_b64 v[128:129], 1, v[148:149]
	v_max_f32_e32 v2, 0, v120
	v_mul_f32_e32 v120, v116, v116
	v_max_f32_e32 v116, 0, v121
	v_mul_f32_e32 v121, v117, v117
	v_max_f32_e32 v117, 0, v122
	v_mul_f32_e32 v122, v118, v118
	v_max_f32_e32 v118, 0, v123
	v_max_f32_e32 v119, 0, v119
	v_lshl_add_u64 v[130:131], v[130:131], 0, v[128:129]
	v_mul_f32_e32 v116, v116, v116
	v_mul_f32_e32 v117, v117, v117
	v_mul_f32_e32 v118, v118, v118
	v_mul_f32_e32 v119, v119, v119
	global_store_dwordx4 v[130:131], v[124:127], off nt
	v_mul_f32_e32 v2, v2, v2
	v_cvt_pk_bf16_f32 v116, v2, v116
	v_cvt_pk_bf16_f32 v117, v117, v118
	v_cvt_pk_bf16_f32 v118, v120, v121
	v_cvt_pk_bf16_f32 v119, v122, v119
	global_store_dwordx4 v[130:131], v[116:119], off offset:256 nt
	s_nop 1
	v_mov_b32_e32 v2, v158
	v_fmamk_f32 v2, v2, 0x3a800000, v208
	v_add_u32_e32 v116, 16, v144
	v_ashrrev_i32_e32 v117, 31, v116
	s_nop 0
	s_nop 1
	s_nop 1
	s_nop 0
	v_rsq_f32_e32 v2, v2
	s_nop 0
	v_pk_mul_f32 v[110:111], v[110:111], v[2:3] op_sel_hi:[1,0]
	v_pk_mul_f32 v[108:109], v[108:109], v[2:3] op_sel_hi:[1,0]
	v_pk_mul_f32 v[114:115], v[114:115], v[2:3] op_sel_hi:[1,0]
	v_pk_mul_f32 v[112:113], v[112:113], v[2:3] op_sel_hi:[1,0]
	v_max_f32_e32 v108, 0, v108
	v_max_f32_e32 v109, 0, v109
	v_max_f32_e32 v110, 0, v110
	v_max_f32_e32 v112, 0, v112
	v_mul_f32_e32 v118, v108, v108
	v_max_f32_e32 v108, 0, v113
	v_mul_f32_e32 v113, v109, v109
	v_max_f32_e32 v109, 0, v114
	v_mul_f32_e32 v114, v110, v110
	v_max_f32_e32 v110, 0, v115
	v_mul_f32_e32 v112, v112, v112
	v_mul_f32_e32 v108, v108, v108
	v_mul_f32_e32 v109, v109, v109
	v_mul_f32_e32 v110, v110, v110
	v_cvt_pk_bf16_f32 v108, v112, v108
	v_cvt_pk_bf16_f32 v109, v109, v110
	v_cvt_pk_bf16_f32 v110, v118, v113
	v_lshlrev_b64 v[112:113], 13, v[116:117]
	v_lshl_add_u64 v[112:113], s[0:1], 0, v[112:113]
	v_pk_mul_f32 v[102:103], v[102:103], v[2:3] op_sel_hi:[1,0]
	v_pk_mul_f32 v[100:101], v[100:101], v[2:3] op_sel_hi:[1,0]
	v_lshl_add_u64 v[112:113], v[112:113], 0, s[26:27]
	v_pk_mul_f32 v[106:107], v[106:107], v[2:3] op_sel_hi:[1,0]
	v_pk_mul_f32 v[104:105], v[104:105], v[2:3] op_sel_hi:[1,0]
	v_max_f32_e32 v100, 0, v100
	v_max_f32_e32 v101, 0, v101
	v_max_f32_e32 v102, 0, v102
	v_max_f32_e32 v111, 0, v111
	v_lshl_add_u64 v[112:113], v[112:113], 0, s[46:47]
	v_max_f32_e32 v2, 0, v104
	v_mul_f32_e32 v104, v100, v100
	v_max_f32_e32 v100, 0, v105
	v_mul_f32_e32 v105, v101, v101
	v_max_f32_e32 v101, 0, v106
	v_mul_f32_e32 v106, v102, v102
	v_max_f32_e32 v102, 0, v107
	v_max_f32_e32 v103, 0, v103
	v_mul_f32_e32 v111, v111, v111
	v_lshl_add_u64 v[112:113], v[112:113], 0, v[128:129]
	v_mul_f32_e32 v100, v100, v100
	v_mul_f32_e32 v101, v101, v101
	v_mul_f32_e32 v102, v102, v102
	v_mul_f32_e32 v103, v103, v103
	v_cvt_pk_bf16_f32 v111, v114, v111
	global_store_dwordx4 v[112:113], v[108:111], off nt
	v_mul_f32_e32 v2, v2, v2
	v_cvt_pk_bf16_f32 v100, v2, v100
	v_cvt_pk_bf16_f32 v101, v101, v102
	v_cvt_pk_bf16_f32 v102, v104, v105
	v_cvt_pk_bf16_f32 v103, v106, v103
	global_store_dwordx4 v[112:113], v[100:103], off offset:256 nt
	s_nop 1
	v_mov_b32_e32 v2, v159
	v_fmamk_f32 v2, v2, 0x3a800000, v208
	v_add_u32_e32 v100, 32, v144
	v_ashrrev_i32_e32 v101, 31, v100
	s_nop 0
	s_nop 1
	s_nop 1
	s_nop 0
	v_rsq_f32_e32 v2, v2
	s_nop 0
	v_pk_mul_f32 v[94:95], v[94:95], v[2:3] op_sel_hi:[1,0]
	v_pk_mul_f32 v[92:93], v[92:93], v[2:3] op_sel_hi:[1,0]
	v_pk_mul_f32 v[98:99], v[98:99], v[2:3] op_sel_hi:[1,0]
	v_pk_mul_f32 v[96:97], v[96:97], v[2:3] op_sel_hi:[1,0]
	v_max_f32_e32 v92, 0, v92
	v_max_f32_e32 v93, 0, v93
	v_max_f32_e32 v94, 0, v94
	v_max_f32_e32 v96, 0, v96
	v_mul_f32_e32 v102, v92, v92
	v_max_f32_e32 v92, 0, v97
	v_mul_f32_e32 v97, v93, v93
	v_max_f32_e32 v93, 0, v98
	v_mul_f32_e32 v98, v94, v94
	v_max_f32_e32 v94, 0, v99
	v_mul_f32_e32 v96, v96, v96
	v_mul_f32_e32 v92, v92, v92
	v_mul_f32_e32 v93, v93, v93
	v_mul_f32_e32 v94, v94, v94
	v_cvt_pk_bf16_f32 v92, v96, v92
	v_cvt_pk_bf16_f32 v93, v93, v94
	v_cvt_pk_bf16_f32 v94, v102, v97
	v_lshlrev_b64 v[96:97], 13, v[100:101]
	v_lshl_add_u64 v[96:97], s[0:1], 0, v[96:97]
	v_pk_mul_f32 v[86:87], v[86:87], v[2:3] op_sel_hi:[1,0]
	v_pk_mul_f32 v[84:85], v[84:85], v[2:3] op_sel_hi:[1,0]
	v_lshl_add_u64 v[96:97], v[96:97], 0, s[26:27]
	v_pk_mul_f32 v[90:91], v[90:91], v[2:3] op_sel_hi:[1,0]
	v_pk_mul_f32 v[88:89], v[88:89], v[2:3] op_sel_hi:[1,0]
	v_max_f32_e32 v84, 0, v84
	v_max_f32_e32 v85, 0, v85
	v_max_f32_e32 v86, 0, v86
	v_max_f32_e32 v95, 0, v95
	v_lshl_add_u64 v[96:97], v[96:97], 0, s[46:47]
	v_max_f32_e32 v2, 0, v88
	v_mul_f32_e32 v88, v84, v84
	v_max_f32_e32 v84, 0, v89
	v_mul_f32_e32 v89, v85, v85
	v_max_f32_e32 v85, 0, v90
	v_mul_f32_e32 v90, v86, v86
	v_max_f32_e32 v86, 0, v91
	v_max_f32_e32 v87, 0, v87
	v_mul_f32_e32 v95, v95, v95
	v_lshl_add_u64 v[96:97], v[96:97], 0, v[128:129]
	v_mul_f32_e32 v84, v84, v84
	v_mul_f32_e32 v85, v85, v85
	v_mul_f32_e32 v86, v86, v86
	v_mul_f32_e32 v87, v87, v87
	v_cvt_pk_bf16_f32 v95, v98, v95
	global_store_dwordx4 v[96:97], v[92:95], off nt
	v_mul_f32_e32 v2, v2, v2
	v_cvt_pk_bf16_f32 v84, v2, v84
	v_cvt_pk_bf16_f32 v85, v85, v86
	v_cvt_pk_bf16_f32 v86, v88, v89
	v_cvt_pk_bf16_f32 v87, v90, v87
	global_store_dwordx4 v[96:97], v[84:87], off offset:256 nt
	s_nop 1
	v_mov_b32_e32 v2, v160
	v_fmamk_f32 v2, v2, 0x3a800000, v208
	v_add_u32_e32 v84, 48, v144
	v_ashrrev_i32_e32 v85, 31, v84
	s_nop 0
	s_nop 1
	s_nop 1
	s_nop 0
	v_rsq_f32_e32 v2, v2
	s_nop 0
	v_pk_mul_f32 v[78:79], v[78:79], v[2:3] op_sel_hi:[1,0]
	v_pk_mul_f32 v[76:77], v[76:77], v[2:3] op_sel_hi:[1,0]
	v_pk_mul_f32 v[82:83], v[82:83], v[2:3] op_sel_hi:[1,0]
	v_pk_mul_f32 v[80:81], v[80:81], v[2:3] op_sel_hi:[1,0]
	v_max_f32_e32 v76, 0, v76
	v_max_f32_e32 v77, 0, v77
	v_max_f32_e32 v78, 0, v78
	v_max_f32_e32 v80, 0, v80
	v_mul_f32_e32 v86, v76, v76
	v_max_f32_e32 v76, 0, v81
	v_mul_f32_e32 v81, v77, v77
	v_max_f32_e32 v77, 0, v82
	v_mul_f32_e32 v82, v78, v78
	v_max_f32_e32 v78, 0, v83
	v_mul_f32_e32 v80, v80, v80
	v_mul_f32_e32 v76, v76, v76
	v_mul_f32_e32 v77, v77, v77
	v_mul_f32_e32 v78, v78, v78
	v_cvt_pk_bf16_f32 v76, v80, v76
	v_cvt_pk_bf16_f32 v77, v77, v78
	v_cvt_pk_bf16_f32 v78, v86, v81
	v_lshlrev_b64 v[80:81], 13, v[84:85]
	v_lshl_add_u64 v[80:81], s[0:1], 0, v[80:81]
	v_pk_mul_f32 v[70:71], v[70:71], v[2:3] op_sel_hi:[1,0]
	v_pk_mul_f32 v[68:69], v[68:69], v[2:3] op_sel_hi:[1,0]
	v_lshl_add_u64 v[80:81], v[80:81], 0, s[26:27]
	v_pk_mul_f32 v[74:75], v[74:75], v[2:3] op_sel_hi:[1,0]
	v_pk_mul_f32 v[72:73], v[72:73], v[2:3] op_sel_hi:[1,0]
	v_max_f32_e32 v68, 0, v68
	v_max_f32_e32 v69, 0, v69
	v_max_f32_e32 v70, 0, v70
	v_max_f32_e32 v79, 0, v79
	v_lshl_add_u64 v[80:81], v[80:81], 0, s[46:47]
	v_max_f32_e32 v2, 0, v72
	v_mul_f32_e32 v72, v68, v68
	v_max_f32_e32 v68, 0, v73
	v_mul_f32_e32 v73, v69, v69
	v_max_f32_e32 v69, 0, v74
	v_mul_f32_e32 v74, v70, v70
	v_max_f32_e32 v70, 0, v75
	v_max_f32_e32 v71, 0, v71
	v_mul_f32_e32 v79, v79, v79
	v_lshl_add_u64 v[80:81], v[80:81], 0, v[128:129]
	v_mul_f32_e32 v68, v68, v68
	v_mul_f32_e32 v69, v69, v69
	v_mul_f32_e32 v70, v70, v70
	v_mul_f32_e32 v71, v71, v71
	v_cvt_pk_bf16_f32 v79, v82, v79
	global_store_dwordx4 v[80:81], v[76:79], off nt
	v_mul_f32_e32 v2, v2, v2
	v_cvt_pk_bf16_f32 v68, v2, v68
	v_cvt_pk_bf16_f32 v69, v69, v70
	v_cvt_pk_bf16_f32 v70, v72, v73
	v_cvt_pk_bf16_f32 v71, v74, v71
	global_store_dwordx4 v[80:81], v[68:71], off offset:256 nt
	s_nop 1
	v_mov_b32_e32 v2, v161
	v_fmamk_f32 v2, v2, 0x3a800000, v208
	v_add_u32_e32 v68, 0x80, v144
	v_ashrrev_i32_e32 v69, 31, v68
	s_nop 0
	s_nop 1
	s_nop 1
	s_nop 0
	v_rsq_f32_e32 v2, v2
	s_nop 0
	v_pk_mul_f32 v[62:63], v[62:63], v[2:3] op_sel_hi:[1,0]
	v_pk_mul_f32 v[60:61], v[60:61], v[2:3] op_sel_hi:[1,0]
	v_pk_mul_f32 v[66:67], v[66:67], v[2:3] op_sel_hi:[1,0]
	v_pk_mul_f32 v[64:65], v[64:65], v[2:3] op_sel_hi:[1,0]
	v_max_f32_e32 v60, 0, v60
	v_max_f32_e32 v61, 0, v61
	v_max_f32_e32 v62, 0, v62
	v_max_f32_e32 v64, 0, v64
	v_mul_f32_e32 v70, v60, v60
	v_max_f32_e32 v60, 0, v65
	v_mul_f32_e32 v65, v61, v61
	v_max_f32_e32 v61, 0, v66
	v_mul_f32_e32 v66, v62, v62
	v_max_f32_e32 v62, 0, v67
	v_mul_f32_e32 v64, v64, v64
	v_mul_f32_e32 v60, v60, v60
	v_mul_f32_e32 v61, v61, v61
	v_mul_f32_e32 v62, v62, v62
	v_cvt_pk_bf16_f32 v60, v64, v60
	v_cvt_pk_bf16_f32 v61, v61, v62
	v_cvt_pk_bf16_f32 v62, v70, v65
	v_lshlrev_b64 v[64:65], 13, v[68:69]
	v_lshl_add_u64 v[64:65], s[0:1], 0, v[64:65]
	v_pk_mul_f32 v[54:55], v[54:55], v[2:3] op_sel_hi:[1,0]
	v_pk_mul_f32 v[52:53], v[52:53], v[2:3] op_sel_hi:[1,0]
	v_lshl_add_u64 v[64:65], v[64:65], 0, s[26:27]
	v_pk_mul_f32 v[58:59], v[58:59], v[2:3] op_sel_hi:[1,0]
	v_pk_mul_f32 v[56:57], v[56:57], v[2:3] op_sel_hi:[1,0]
	v_max_f32_e32 v52, 0, v52
	v_max_f32_e32 v53, 0, v53
	v_max_f32_e32 v54, 0, v54
	v_max_f32_e32 v63, 0, v63
	v_lshl_add_u64 v[64:65], v[64:65], 0, s[46:47]
	v_max_f32_e32 v2, 0, v56
	v_mul_f32_e32 v56, v52, v52
	v_max_f32_e32 v52, 0, v57
	v_mul_f32_e32 v57, v53, v53
	v_max_f32_e32 v53, 0, v58
	v_mul_f32_e32 v58, v54, v54
	v_max_f32_e32 v54, 0, v59
	v_max_f32_e32 v55, 0, v55
	v_mul_f32_e32 v63, v63, v63
	v_lshl_add_u64 v[64:65], v[64:65], 0, v[128:129]
	v_mul_f32_e32 v52, v52, v52
	v_mul_f32_e32 v53, v53, v53
	v_mul_f32_e32 v54, v54, v54
	v_mul_f32_e32 v55, v55, v55
	v_cvt_pk_bf16_f32 v63, v66, v63
	global_store_dwordx4 v[64:65], v[60:63], off nt
	v_mul_f32_e32 v2, v2, v2
	v_cvt_pk_bf16_f32 v52, v2, v52
	v_cvt_pk_bf16_f32 v53, v53, v54
	v_cvt_pk_bf16_f32 v54, v56, v57
	v_cvt_pk_bf16_f32 v55, v58, v55
	global_store_dwordx4 v[64:65], v[52:55], off offset:256 nt
	s_nop 1
	v_mov_b32_e32 v2, v162
	v_fmamk_f32 v2, v2, 0x3a800000, v208
	v_add_u32_e32 v52, 0x90, v144
	v_ashrrev_i32_e32 v53, 31, v52
	s_nop 0
	s_nop 1
	s_nop 1
	s_nop 0
	v_rsq_f32_e32 v2, v2
	s_nop 0
	v_pk_mul_f32 v[46:47], v[46:47], v[2:3] op_sel_hi:[1,0]
	v_pk_mul_f32 v[44:45], v[44:45], v[2:3] op_sel_hi:[1,0]
	v_pk_mul_f32 v[50:51], v[50:51], v[2:3] op_sel_hi:[1,0]
	v_pk_mul_f32 v[48:49], v[48:49], v[2:3] op_sel_hi:[1,0]
	v_max_f32_e32 v44, 0, v44
	v_max_f32_e32 v45, 0, v45
	v_max_f32_e32 v46, 0, v46
	v_max_f32_e32 v48, 0, v48
	v_mul_f32_e32 v54, v44, v44
	v_max_f32_e32 v44, 0, v49
	v_mul_f32_e32 v49, v45, v45
	v_max_f32_e32 v45, 0, v50
	v_mul_f32_e32 v50, v46, v46
	v_max_f32_e32 v46, 0, v51
	v_mul_f32_e32 v48, v48, v48
	v_mul_f32_e32 v44, v44, v44
	v_mul_f32_e32 v45, v45, v45
	v_mul_f32_e32 v46, v46, v46
	v_cvt_pk_bf16_f32 v44, v48, v44
	v_cvt_pk_bf16_f32 v45, v45, v46
	v_cvt_pk_bf16_f32 v46, v54, v49
	v_lshlrev_b64 v[48:49], 13, v[52:53]
	v_lshl_add_u64 v[48:49], s[0:1], 0, v[48:49]
	v_pk_mul_f32 v[38:39], v[38:39], v[2:3] op_sel_hi:[1,0]
	v_pk_mul_f32 v[36:37], v[36:37], v[2:3] op_sel_hi:[1,0]
	v_lshl_add_u64 v[48:49], v[48:49], 0, s[26:27]
	v_pk_mul_f32 v[42:43], v[42:43], v[2:3] op_sel_hi:[1,0]
	v_pk_mul_f32 v[40:41], v[40:41], v[2:3] op_sel_hi:[1,0]
	v_max_f32_e32 v36, 0, v36
	v_max_f32_e32 v37, 0, v37
	v_max_f32_e32 v38, 0, v38
	v_max_f32_e32 v47, 0, v47
	v_lshl_add_u64 v[48:49], v[48:49], 0, s[46:47]
	v_max_f32_e32 v2, 0, v40
	v_mul_f32_e32 v40, v36, v36
	v_max_f32_e32 v36, 0, v41
	v_mul_f32_e32 v41, v37, v37
	v_max_f32_e32 v37, 0, v42
	v_mul_f32_e32 v42, v38, v38
	v_max_f32_e32 v38, 0, v43
	v_max_f32_e32 v39, 0, v39
	v_mul_f32_e32 v47, v47, v47
	v_lshl_add_u64 v[48:49], v[48:49], 0, v[128:129]
	v_mul_f32_e32 v36, v36, v36
	v_mul_f32_e32 v37, v37, v37
	v_mul_f32_e32 v38, v38, v38
	v_mul_f32_e32 v39, v39, v39
	v_cvt_pk_bf16_f32 v47, v50, v47
	global_store_dwordx4 v[48:49], v[44:47], off nt
	v_mul_f32_e32 v2, v2, v2
	v_cvt_pk_bf16_f32 v36, v2, v36
	v_cvt_pk_bf16_f32 v37, v37, v38
	v_cvt_pk_bf16_f32 v38, v40, v41
	v_cvt_pk_bf16_f32 v39, v42, v39
	global_store_dwordx4 v[48:49], v[36:39], off offset:256 nt
	s_nop 1
	v_mov_b32_e32 v2, v163
	v_fmamk_f32 v2, v2, 0x3a800000, v208
	v_add_u32_e32 v36, 0xa0, v144
	v_ashrrev_i32_e32 v37, 31, v36
	s_nop 0
	s_nop 1
	s_nop 1
	s_nop 0
	v_rsq_f32_e32 v2, v2
	s_nop 0
	v_pk_mul_f32 v[30:31], v[30:31], v[2:3] op_sel_hi:[1,0]
	v_pk_mul_f32 v[28:29], v[28:29], v[2:3] op_sel_hi:[1,0]
	v_pk_mul_f32 v[34:35], v[34:35], v[2:3] op_sel_hi:[1,0]
	v_pk_mul_f32 v[32:33], v[32:33], v[2:3] op_sel_hi:[1,0]
	v_max_f32_e32 v28, 0, v28
	v_max_f32_e32 v29, 0, v29
	v_max_f32_e32 v30, 0, v30
	v_max_f32_e32 v32, 0, v32
	v_mul_f32_e32 v38, v28, v28
	v_max_f32_e32 v28, 0, v33
	v_mul_f32_e32 v33, v29, v29
	v_max_f32_e32 v29, 0, v34
	v_mul_f32_e32 v34, v30, v30
	v_max_f32_e32 v30, 0, v35
	v_mul_f32_e32 v32, v32, v32
	v_mul_f32_e32 v28, v28, v28
	v_mul_f32_e32 v29, v29, v29
	v_mul_f32_e32 v30, v30, v30
	v_cvt_pk_bf16_f32 v28, v32, v28
	v_cvt_pk_bf16_f32 v29, v29, v30
	v_cvt_pk_bf16_f32 v30, v38, v33
	v_lshlrev_b64 v[32:33], 13, v[36:37]
	v_lshl_add_u64 v[32:33], s[0:1], 0, v[32:33]
	v_pk_mul_f32 v[22:23], v[22:23], v[2:3] op_sel_hi:[1,0]
	v_pk_mul_f32 v[20:21], v[20:21], v[2:3] op_sel_hi:[1,0]
	v_lshl_add_u64 v[32:33], v[32:33], 0, s[26:27]
	v_pk_mul_f32 v[26:27], v[26:27], v[2:3] op_sel_hi:[1,0]
	v_pk_mul_f32 v[24:25], v[24:25], v[2:3] op_sel_hi:[1,0]
	v_max_f32_e32 v20, 0, v20
	v_max_f32_e32 v21, 0, v21
	v_max_f32_e32 v22, 0, v22
	v_max_f32_e32 v31, 0, v31
	v_lshl_add_u64 v[32:33], v[32:33], 0, s[46:47]
	v_max_f32_e32 v2, 0, v24
	v_mul_f32_e32 v24, v20, v20
	v_max_f32_e32 v20, 0, v25
	v_mul_f32_e32 v25, v21, v21
	v_max_f32_e32 v21, 0, v26
	v_mul_f32_e32 v26, v22, v22
	v_max_f32_e32 v22, 0, v27
	v_max_f32_e32 v23, 0, v23
	v_mul_f32_e32 v31, v31, v31
	v_lshl_add_u64 v[32:33], v[32:33], 0, v[128:129]
	v_mul_f32_e32 v20, v20, v20
	v_mul_f32_e32 v21, v21, v21
	v_mul_f32_e32 v22, v22, v22
	v_mul_f32_e32 v23, v23, v23
	v_cvt_pk_bf16_f32 v31, v34, v31
	global_store_dwordx4 v[32:33], v[28:31], off nt
	v_mul_f32_e32 v2, v2, v2
	v_cvt_pk_bf16_f32 v20, v2, v20
	v_cvt_pk_bf16_f32 v21, v21, v22
	v_cvt_pk_bf16_f32 v22, v24, v25
	v_cvt_pk_bf16_f32 v23, v26, v23
	global_store_dwordx4 v[32:33], v[20:23], off offset:256 nt
	s_nop 1
	v_mov_b32_e32 v2, v164
	v_fmamk_f32 v2, v2, 0x3a800000, v208
	v_add_u32_e32 v20, 0xb0, v144
	v_ashrrev_i32_e32 v21, 31, v20
	s_nop 0
	s_nop 1
	s_nop 1
	s_mov_b64 s[4:5], -1
	v_rsq_f32_e32 v2, v2
	s_nop 0
	v_pk_mul_f32 v[14:15], v[14:15], v[2:3] op_sel_hi:[1,0]
	v_pk_mul_f32 v[12:13], v[12:13], v[2:3] op_sel_hi:[1,0]
	v_pk_mul_f32 v[18:19], v[18:19], v[2:3] op_sel_hi:[1,0]
	v_pk_mul_f32 v[16:17], v[16:17], v[2:3] op_sel_hi:[1,0]
	v_max_f32_e32 v12, 0, v12
	v_max_f32_e32 v13, 0, v13
	v_max_f32_e32 v14, 0, v14
	v_max_f32_e32 v16, 0, v16
	v_mul_f32_e32 v22, v12, v12
	v_max_f32_e32 v12, 0, v17
	v_mul_f32_e32 v17, v13, v13
	v_max_f32_e32 v13, 0, v18
	v_mul_f32_e32 v18, v14, v14
	v_max_f32_e32 v14, 0, v19
	v_mul_f32_e32 v16, v16, v16
	v_mul_f32_e32 v12, v12, v12
	v_mul_f32_e32 v13, v13, v13
	v_mul_f32_e32 v14, v14, v14
	v_cvt_pk_bf16_f32 v12, v16, v12
	v_cvt_pk_bf16_f32 v13, v13, v14
	v_cvt_pk_bf16_f32 v14, v22, v17
	v_lshlrev_b64 v[16:17], 13, v[20:21]
	v_lshl_add_u64 v[16:17], s[0:1], 0, v[16:17]
	v_pk_mul_f32 v[6:7], v[6:7], v[2:3] op_sel_hi:[1,0]
	v_pk_mul_f32 v[4:5], v[4:5], v[2:3] op_sel_hi:[1,0]
	v_lshl_add_u64 v[16:17], v[16:17], 0, s[26:27]
	v_pk_mul_f32 v[10:11], v[10:11], v[2:3] op_sel_hi:[1,0]
	v_pk_mul_f32 v[8:9], v[8:9], v[2:3] op_sel_hi:[1,0]
	v_max_f32_e32 v4, 0, v4
	v_max_f32_e32 v5, 0, v5
	v_max_f32_e32 v6, 0, v6
	v_max_f32_e32 v15, 0, v15
	v_lshl_add_u64 v[16:17], v[16:17], 0, s[46:47]
	v_max_f32_e32 v2, 0, v8
	v_mul_f32_e32 v8, v4, v4
	v_max_f32_e32 v4, 0, v9
	v_mul_f32_e32 v9, v5, v5
	v_max_f32_e32 v5, 0, v10
	v_mul_f32_e32 v10, v6, v6
	v_max_f32_e32 v6, 0, v11
	v_max_f32_e32 v7, 0, v7
	v_mul_f32_e32 v15, v15, v15
	v_lshl_add_u64 v[16:17], v[16:17], 0, v[128:129]
	v_mul_f32_e32 v4, v4, v4
	v_mul_f32_e32 v5, v5, v5
	v_mul_f32_e32 v6, v6, v6
	v_mul_f32_e32 v7, v7, v7
	v_cvt_pk_bf16_f32 v15, v18, v15
	global_store_dwordx4 v[16:17], v[12:15], off nt
	v_mul_f32_e32 v2, v2, v2
	v_cvt_pk_bf16_f32 v4, v2, v4
	v_cvt_pk_bf16_f32 v5, v5, v6
	v_cvt_pk_bf16_f32 v6, v8, v9
	v_cvt_pk_bf16_f32 v7, v10, v7
	global_store_dwordx4 v[16:17], v[4:7], off offset:256 nt
	s_cbranch_scc1 .LBB0_2536
	s_andn2_b64 vcc, exec, s[14:15]
	s_cbranch_vccnz .LBB0_2535
	s_barrier
	s_branch .LBB0_2535
